# v21: v15 plus the GLA state scan runs on workgroups 256..511 (which have one fewer MLA up-projection tile in that phase) when the grid has 512 workgroups
# baseline (speedup 1.0000x reference)
; DI int tidx() { int t = threadIdx.x; asm volatile("" : "+v"(t)); return t; }
; DI void gla_pass2(float* __restrict__ Ubuf, const float* __restrict__ Ebuf) {
;   const int idx = blockIdx.x * 256 + tidx();
;   if (idx < 32 * 64 * 32) {
;     const int bh = idx >> 11, d = (idx >> 5) & 63, v4 = idx & 31;
;     f32x4 S = (f32x4){0.f, 0.f, 0.f, 0.f};
; #pragma unroll 8
;     for (int n = 0; n < 32; ++n) {
;       float* p = Ubuf + (((size_t)bh * 32 + n) * 64 + d) * 128 + v4 * 4;
;       const f32x4 u = *(const f32x4*)p;
;       const float e = Ebuf[((size_t)bh * 32 + n) * 64 + d];
;       *(f32x4*)p = S;
;       S = e * (S + u);
;     }
;   }
.LBB0_877:
	s_or_b64 exec, exec, s[0:1]
	v_mov_b32_e32 v0, v190
	v_readlane_b32 s0, v253, 3
	s_waitcnt lgkmcnt(0)
	s_barrier
	s_nop 0
	v_add_u32_e32 v2, s0, v0
	v_readlane_b32 s100, v253, 52
	s_cmpk_lt_u32 s100, 0x200
	s_cselect_b32 s100, 0, 0x10000
	s_nop 0
	v_subrev_u32_e32 v2, s100, v2
	s_mov_b32 s0, 0x10000
	v_cmp_gt_u32_e32 vcc, s0, v2
	s_and_saveexec_b64 s[0:1], vcc
	s_mov_b64 s[6:7], 0x40000
	s_cbranch_execz .LBB0_880
	v_ashrrev_i32_e32 v4, 11, v2
	v_ashrrev_i32_e32 v5, 31, v4
	v_bfe_u32 v2, v2, 5, 6
	v_lshlrev_b64 v[6:7], 13, v[4:5]
	v_and_b32_e32 v0, 31, v0
	v_lshl_or_b32 v6, v2, 2, v6
	v_lshlrev_b64 v[8:9], 20, v[4:5]
	v_lshlrev_b32_e32 v2, 9, v2
	v_lshlrev_b32_e32 v0, 4, v0
	v_or3_b32 v8, v8, v2, v0
	v_mov_b32_e32 v2, 0
	s_mov_b32 s2, 32
	v_mov_b32_e32 v3, v2
	v_mov_b32_e32 v4, v2
	v_mov_b32_e32 v5, v2
